# down-GEMM epilogue: paired 8-byte result stores merged into 16-byte stores via v_permlane16_swap
# baseline (speedup 1.0000x reference)
.LBB0_2188:
	ds_read_b128 v[136:139], v195
	ds_read_b128 v[140:143], v195 offset:1024
	ds_read_b128 v[144:147], v195 offset:2048
	ds_read_b128 v[148:151], v195 offset:3072
	s_add_u32 s43, s26, 0xfff58080
	s_addc_u32 s44, s27, -1
	s_cmp_eq_u32 s42, 38
	s_cselect_b32 s45, s23, s44
	s_cselect_b32 s44, s22, s43
	s_cselect_b32 s59, s25, s29
	s_cselect_b32 s58, s24, s28
	v_lshl_add_u64 v[184:185], s[26:27], 0, v[130:131]
	s_add_i32 m0, s36, 0xc000
	ds_read_b128 v[152:155], v196
	ds_read_b128 v[156:159], v196 offset:1024
	ds_read_b128 v[160:163], v196 offset:2048
	ds_read_b128 v[164:167], v196 offset:3072
	ds_read_b128 v[168:171], v196 offset:4096
	ds_read_b128 v[172:175], v196 offset:5120
	ds_read_b128 v[176:179], v196 offset:6144
	ds_read_b128 v[180:183], v196 offset:7168
	global_load_lds_dwordx4 v[184:185], off
	v_lshl_add_u64 v[184:185], v[184:185], 0, s[6:7]
	s_add_i32 m0, s36, 0xe000
	s_nop 0
	global_load_lds_dwordx4 v[184:185], off
	s_waitcnt lgkmcnt(8)
	s_barrier
	s_waitcnt lgkmcnt(0)
	s_setprio 1
	s_waitcnt lgkmcnt(0)
	v_mfma_f32_16x16x32_bf16 v[124:127], v[136:139], v[152:155], v[124:127]
	v_mfma_f32_16x16x32_bf16 v[120:123], v[144:147], v[152:155], v[120:123]
	v_mfma_f32_16x16x32_bf16 v[112:115], v[136:139], v[160:163], v[112:115]
	v_mfma_f32_16x16x32_bf16 v[104:107], v[144:147], v[160:163], v[104:107]
	v_mfma_f32_16x16x32_bf16 v[96:99], v[136:139], v[168:171], v[96:99]
	v_mfma_f32_16x16x32_bf16 v[88:91], v[144:147], v[168:171], v[88:91]
	v_mfma_f32_16x16x32_bf16 v[80:83], v[136:139], v[176:179], v[80:83]
	v_mfma_f32_16x16x32_bf16 v[72:75], v[144:147], v[176:179], v[72:75]
	v_mfma_f32_16x16x32_bf16 v[124:127], v[140:143], v[156:159], v[124:127]
	v_mfma_f32_16x16x32_bf16 v[120:123], v[148:151], v[156:159], v[120:123]
	v_mfma_f32_16x16x32_bf16 v[112:115], v[140:143], v[164:167], v[112:115]
	v_mfma_f32_16x16x32_bf16 v[104:107], v[148:151], v[164:167], v[104:107]
	v_mfma_f32_16x16x32_bf16 v[96:99], v[140:143], v[172:175], v[96:99]
	v_mfma_f32_16x16x32_bf16 v[88:91], v[148:151], v[172:175], v[88:91]
	v_mfma_f32_16x16x32_bf16 v[80:83], v[140:143], v[180:183], v[80:83]
	v_mfma_f32_16x16x32_bf16 v[72:75], v[148:151], v[180:183], v[72:75]
	s_setprio 0
	s_barrier
	s_add_i32 s43, s51, s35
	v_lshl_add_u64 v[192:193], s[58:59], 0, v[128:129]
	s_mov_b32 m0, s43
	ds_read_b128 v[184:187], v197
	ds_read_b128 v[188:191], v197 offset:1024
	ds_read_b128 v[198:201], v197 offset:2048
	ds_read_b128 v[202:205], v197 offset:3072
	global_load_lds_dwordx4 v[192:193], off
	v_lshl_add_u64 v[206:207], v[192:193], 0, s[6:7]
	s_add_i32 m0, s43, 0x2000
	s_nop 0
	global_load_lds_dwordx4 v[206:207], off
	s_barrier
	s_waitcnt lgkmcnt(0)
	s_setprio 1
	s_waitcnt lgkmcnt(0)
	v_mfma_f32_16x16x32_bf16 v[116:119], v[184:187], v[152:155], v[116:119]
	v_mfma_f32_16x16x32_bf16 v[108:111], v[198:201], v[152:155], v[108:111]
	v_mfma_f32_16x16x32_bf16 v[100:103], v[184:187], v[160:163], v[100:103]
	v_mfma_f32_16x16x32_bf16 v[92:95], v[198:201], v[160:163], v[92:95]
	v_mfma_f32_16x16x32_bf16 v[84:87], v[184:187], v[168:171], v[84:87]
	v_mfma_f32_16x16x32_bf16 v[76:79], v[198:201], v[168:171], v[76:79]
	v_mfma_f32_16x16x32_bf16 v[68:71], v[184:187], v[176:179], v[68:71]
	v_mfma_f32_16x16x32_bf16 v[64:67], v[198:201], v[176:179], v[64:67]
	v_mfma_f32_16x16x32_bf16 v[116:119], v[188:191], v[156:159], v[116:119]
	v_mfma_f32_16x16x32_bf16 v[108:111], v[202:205], v[156:159], v[108:111]
	v_mfma_f32_16x16x32_bf16 v[100:103], v[188:191], v[164:167], v[100:103]
	v_mfma_f32_16x16x32_bf16 v[92:95], v[202:205], v[164:167], v[92:95]
	v_mfma_f32_16x16x32_bf16 v[84:87], v[188:191], v[172:175], v[84:87]
	v_mfma_f32_16x16x32_bf16 v[76:79], v[202:205], v[172:175], v[76:79]
	v_mfma_f32_16x16x32_bf16 v[68:71], v[188:191], v[180:183], v[68:71]
	v_mfma_f32_16x16x32_bf16 v[64:67], v[202:205], v[180:183], v[64:67]
	s_setprio 0
	s_mov_b32 m0, s36
	v_lshl_add_u64 v[206:207], s[44:45], 0, v[128:129]
	s_barrier
	ds_read_b128 v[152:155], v196 offset:16384
	ds_read_b128 v[156:159], v196 offset:17408
	ds_read_b128 v[160:163], v196 offset:18432
	ds_read_b128 v[164:167], v196 offset:19456
	ds_read_b128 v[168:171], v196 offset:20480
	ds_read_b128 v[172:175], v196 offset:21504
	ds_read_b128 v[176:179], v196 offset:22528
	ds_read_b128 v[180:183], v196 offset:23552
	global_load_lds_dwordx4 v[206:207], off
	v_lshl_add_u64 v[208:209], v[206:207], 0, s[6:7]
	s_mov_b32 m0, s37
	s_nop 0
	global_load_lds_dwordx4 v[208:209], off
	s_barrier
	s_waitcnt lgkmcnt(0)
	s_setprio 1
	s_waitcnt lgkmcnt(0)
	v_mfma_f32_16x16x32_bf16 v[60:63], v[136:139], v[152:155], v[60:63]
	v_mfma_f32_16x16x32_bf16 v[56:59], v[144:147], v[152:155], v[56:59]
	v_mfma_f32_16x16x32_bf16 v[48:51], v[136:139], v[160:163], v[48:51]
	v_mfma_f32_16x16x32_bf16 v[40:43], v[144:147], v[160:163], v[40:43]
	v_mfma_f32_16x16x32_bf16 v[32:35], v[136:139], v[168:171], v[32:35]
	v_mfma_f32_16x16x32_bf16 v[24:27], v[144:147], v[168:171], v[24:27]
	v_mfma_f32_16x16x32_bf16 v[16:19], v[136:139], v[176:179], v[16:19]
	v_mfma_f32_16x16x32_bf16 v[8:11], v[144:147], v[176:179], v[8:11]
	v_mfma_f32_16x16x32_bf16 v[60:63], v[140:143], v[156:159], v[60:63]
	v_mfma_f32_16x16x32_bf16 v[56:59], v[148:151], v[156:159], v[56:59]
	v_mfma_f32_16x16x32_bf16 v[48:51], v[140:143], v[164:167], v[48:51]
	v_mfma_f32_16x16x32_bf16 v[40:43], v[148:151], v[164:167], v[40:43]
	v_mfma_f32_16x16x32_bf16 v[32:35], v[140:143], v[172:175], v[32:35]
	v_mfma_f32_16x16x32_bf16 v[24:27], v[148:151], v[172:175], v[24:27]
	v_mfma_f32_16x16x32_bf16 v[16:19], v[140:143], v[180:183], v[16:19]
	v_mfma_f32_16x16x32_bf16 v[8:11], v[148:151], v[180:183], v[8:11]
	s_setprio 0
	s_barrier
	s_add_i32 s43, s52, s35
	v_lshl_add_u64 v[136:137], v[192:193], 0, s[8:9]
	s_mov_b32 m0, s43
	s_nop 0
	global_load_lds_dwordx4 v[136:137], off
	v_lshl_add_u64 v[136:137], v[192:193], 0, s[10:11]
	s_add_i32 m0, s43, 0x2000
	s_nop 0
	global_load_lds_dwordx4 v[136:137], off
	s_waitcnt vmcnt(6)
	s_barrier
	s_setprio 1
	v_mfma_f32_16x16x32_bf16 v[52:55], v[184:187], v[152:155], v[52:55]
	v_mfma_f32_16x16x32_bf16 v[44:47], v[198:201], v[152:155], v[44:47]
	v_mfma_f32_16x16x32_bf16 v[36:39], v[184:187], v[160:163], v[36:39]
	v_mfma_f32_16x16x32_bf16 v[28:31], v[198:201], v[160:163], v[28:31]
	v_mfma_f32_16x16x32_bf16 v[20:23], v[184:187], v[168:171], v[20:23]
	v_mfma_f32_16x16x32_bf16 v[12:15], v[198:201], v[168:171], v[12:15]
	v_mfma_f32_16x16x32_bf16 v[4:7], v[184:187], v[176:179], v[4:7]
	v_mfma_f32_16x16x32_bf16 v[0:3], v[198:201], v[176:179], v[0:3]
	v_mfma_f32_16x16x32_bf16 v[52:55], v[188:191], v[156:159], v[52:55]
	v_mfma_f32_16x16x32_bf16 v[44:47], v[202:205], v[156:159], v[44:47]
	v_mfma_f32_16x16x32_bf16 v[36:39], v[188:191], v[164:167], v[36:39]
	v_mfma_f32_16x16x32_bf16 v[28:31], v[202:205], v[164:167], v[28:31]
	v_mfma_f32_16x16x32_bf16 v[20:23], v[188:191], v[172:175], v[20:23]
	v_mfma_f32_16x16x32_bf16 v[12:15], v[202:205], v[172:175], v[12:15]
	v_mfma_f32_16x16x32_bf16 v[4:7], v[188:191], v[180:183], v[4:7]
	v_mfma_f32_16x16x32_bf16 v[0:3], v[202:205], v[180:183], v[0:3]
	s_setprio 0
	s_add_i32 s43, 0, 0x18000
	v_add_u32_e32 v148, s43, v194
	s_barrier
	ds_read_b128 v[136:139], v148
	ds_read_b128 v[140:143], v148 offset:1024
	ds_read_b128 v[144:147], v148 offset:2048
	ds_read_b128 v[148:151], v148 offset:3072
	s_mov_b32 m0, s38
	v_lshl_add_u64 v[184:185], v[206:207], 0, s[8:9]
	ds_read_b128 v[152:155], v196 offset:32768
	ds_read_b128 v[156:159], v196 offset:33792
	ds_read_b128 v[160:163], v196 offset:34816
	ds_read_b128 v[164:167], v196 offset:35840
	ds_read_b128 v[168:171], v196 offset:36864
	ds_read_b128 v[172:175], v196 offset:37888
	ds_read_b128 v[176:179], v196 offset:38912
	ds_read_b128 v[180:183], v196 offset:39936
	global_load_lds_dwordx4 v[184:185], off
	v_lshl_add_u64 v[184:185], v[206:207], 0, s[10:11]
	s_mov_b32 m0, s39
	s_nop 0
	global_load_lds_dwordx4 v[184:185], off
	s_waitcnt lgkmcnt(8)
	s_barrier
	s_waitcnt lgkmcnt(0)
	s_setprio 1
	s_waitcnt lgkmcnt(0)
	v_mfma_f32_16x16x32_bf16 v[124:127], v[136:139], v[152:155], v[124:127]
	v_mfma_f32_16x16x32_bf16 v[120:123], v[144:147], v[152:155], v[120:123]
	v_mfma_f32_16x16x32_bf16 v[112:115], v[136:139], v[160:163], v[112:115]
	v_mfma_f32_16x16x32_bf16 v[104:107], v[144:147], v[160:163], v[104:107]
	v_mfma_f32_16x16x32_bf16 v[96:99], v[136:139], v[168:171], v[96:99]
	v_mfma_f32_16x16x32_bf16 v[88:91], v[144:147], v[168:171], v[88:91]
	v_mfma_f32_16x16x32_bf16 v[80:83], v[136:139], v[176:179], v[80:83]
	v_mfma_f32_16x16x32_bf16 v[72:75], v[144:147], v[176:179], v[72:75]
	v_mfma_f32_16x16x32_bf16 v[124:127], v[140:143], v[156:159], v[124:127]
	v_mfma_f32_16x16x32_bf16 v[120:123], v[148:151], v[156:159], v[120:123]
	v_mfma_f32_16x16x32_bf16 v[112:115], v[140:143], v[164:167], v[112:115]
	v_mfma_f32_16x16x32_bf16 v[104:107], v[148:151], v[164:167], v[104:107]
	v_mfma_f32_16x16x32_bf16 v[96:99], v[140:143], v[172:175], v[96:99]
	v_mfma_f32_16x16x32_bf16 v[88:91], v[148:151], v[172:175], v[88:91]
	v_mfma_f32_16x16x32_bf16 v[80:83], v[140:143], v[180:183], v[80:83]
	v_mfma_f32_16x16x32_bf16 v[72:75], v[148:151], v[180:183], v[72:75]
	s_setprio 0
	s_barrier
	s_add_i32 s44, 0, 0x1c000
	s_add_i32 s43, s43, s35
	v_add_u32_e32 v202, s44, v194
	v_lshl_add_u64 v[208:209], v[192:193], 0, s[12:13]
	s_mov_b32 m0, s43
	ds_read_b128 v[184:187], v202
	ds_read_b128 v[188:191], v202 offset:1024
	ds_read_b128 v[198:201], v202 offset:2048
	ds_read_b128 v[202:205], v202 offset:3072
	global_load_lds_dwordx4 v[208:209], off
	v_lshl_add_u64 v[208:209], v[192:193], 0, s[14:15]
	s_add_i32 m0, s43, 0x2000
	s_nop 0
	global_load_lds_dwordx4 v[208:209], off
	s_barrier
	s_waitcnt lgkmcnt(0)
	s_setprio 1
	s_waitcnt lgkmcnt(0)
	v_mfma_f32_16x16x32_bf16 v[116:119], v[184:187], v[152:155], v[116:119]
	v_mfma_f32_16x16x32_bf16 v[108:111], v[198:201], v[152:155], v[108:111]
	v_mfma_f32_16x16x32_bf16 v[100:103], v[184:187], v[160:163], v[100:103]
	v_mfma_f32_16x16x32_bf16 v[92:95], v[198:201], v[160:163], v[92:95]
	v_mfma_f32_16x16x32_bf16 v[84:87], v[184:187], v[168:171], v[84:87]
	v_mfma_f32_16x16x32_bf16 v[76:79], v[198:201], v[168:171], v[76:79]
	v_mfma_f32_16x16x32_bf16 v[68:71], v[184:187], v[176:179], v[68:71]
	v_mfma_f32_16x16x32_bf16 v[64:67], v[198:201], v[176:179], v[64:67]
	v_mfma_f32_16x16x32_bf16 v[116:119], v[188:191], v[156:159], v[116:119]
	v_mfma_f32_16x16x32_bf16 v[108:111], v[202:205], v[156:159], v[108:111]
	v_mfma_f32_16x16x32_bf16 v[100:103], v[188:191], v[164:167], v[100:103]
	v_mfma_f32_16x16x32_bf16 v[92:95], v[202:205], v[164:167], v[92:95]
	v_mfma_f32_16x16x32_bf16 v[84:87], v[188:191], v[172:175], v[84:87]
	v_mfma_f32_16x16x32_bf16 v[76:79], v[202:205], v[172:175], v[76:79]
	v_mfma_f32_16x16x32_bf16 v[68:71], v[188:191], v[180:183], v[68:71]
	v_mfma_f32_16x16x32_bf16 v[64:67], v[202:205], v[180:183], v[64:67]
	s_setprio 0
	s_mov_b32 m0, s49
	v_lshl_add_u64 v[208:209], v[206:207], 0, s[12:13]
	s_barrier
	ds_read_b128 v[152:155], v196 offset:49152
	ds_read_b128 v[156:159], v196 offset:50176
	ds_read_b128 v[160:163], v196 offset:51200
	ds_read_b128 v[164:167], v196 offset:52224
	ds_read_b128 v[168:171], v196 offset:53248
	ds_read_b128 v[172:175], v196 offset:54272
	ds_read_b128 v[176:179], v196 offset:55296
	ds_read_b128 v[180:183], v196 offset:56320
	global_load_lds_dwordx4 v[208:209], off
	v_lshl_add_u64 v[206:207], v[206:207], 0, s[14:15]
	s_mov_b32 m0, s50
	s_nop 0
	global_load_lds_dwordx4 v[206:207], off
	s_barrier
	s_waitcnt lgkmcnt(0)
	s_setprio 1
	s_waitcnt lgkmcnt(0)
	v_mfma_f32_16x16x32_bf16 v[60:63], v[136:139], v[152:155], v[60:63]
	v_mfma_f32_16x16x32_bf16 v[56:59], v[144:147], v[152:155], v[56:59]
	v_mfma_f32_16x16x32_bf16 v[48:51], v[136:139], v[160:163], v[48:51]
	v_mfma_f32_16x16x32_bf16 v[40:43], v[144:147], v[160:163], v[40:43]
	v_mfma_f32_16x16x32_bf16 v[32:35], v[136:139], v[168:171], v[32:35]
	v_mfma_f32_16x16x32_bf16 v[24:27], v[144:147], v[168:171], v[24:27]
	v_mfma_f32_16x16x32_bf16 v[16:19], v[136:139], v[176:179], v[16:19]
	v_mfma_f32_16x16x32_bf16 v[8:11], v[144:147], v[176:179], v[8:11]
	v_mfma_f32_16x16x32_bf16 v[60:63], v[140:143], v[156:159], v[60:63]
	v_mfma_f32_16x16x32_bf16 v[56:59], v[148:151], v[156:159], v[56:59]
	v_mfma_f32_16x16x32_bf16 v[48:51], v[140:143], v[164:167], v[48:51]
	v_mfma_f32_16x16x32_bf16 v[40:43], v[148:151], v[164:167], v[40:43]
	v_mfma_f32_16x16x32_bf16 v[32:35], v[140:143], v[172:175], v[32:35]
	v_mfma_f32_16x16x32_bf16 v[24:27], v[148:151], v[172:175], v[24:27]
	v_mfma_f32_16x16x32_bf16 v[16:19], v[140:143], v[180:183], v[16:19]
	v_mfma_f32_16x16x32_bf16 v[8:11], v[148:151], v[180:183], v[8:11]
	s_setprio 0
	s_barrier
	s_add_i32 s43, s44, s35
	v_lshl_add_u64 v[136:137], v[192:193], 0, s[16:17]
	s_mov_b32 m0, s43
	s_nop 0
	global_load_lds_dwordx4 v[136:137], off
	v_lshl_add_u64 v[136:137], v[192:193], 0, s[18:19]
	s_add_i32 m0, s43, 0x2000
	s_nop 0
	global_load_lds_dwordx4 v[136:137], off
	s_waitcnt vmcnt(6)
	s_barrier
	s_setprio 1
	v_mfma_f32_16x16x32_bf16 v[52:55], v[184:187], v[152:155], v[52:55]
	v_mfma_f32_16x16x32_bf16 v[44:47], v[198:201], v[152:155], v[44:47]
	v_mfma_f32_16x16x32_bf16 v[36:39], v[184:187], v[160:163], v[36:39]
	v_mfma_f32_16x16x32_bf16 v[28:31], v[198:201], v[160:163], v[28:31]
	v_mfma_f32_16x16x32_bf16 v[20:23], v[184:187], v[168:171], v[20:23]
	v_mfma_f32_16x16x32_bf16 v[12:15], v[198:201], v[168:171], v[12:15]
	v_mfma_f32_16x16x32_bf16 v[4:7], v[184:187], v[176:179], v[4:7]
	v_mfma_f32_16x16x32_bf16 v[0:3], v[198:201], v[176:179], v[0:3]
	v_mfma_f32_16x16x32_bf16 v[52:55], v[188:191], v[156:159], v[52:55]
	v_mfma_f32_16x16x32_bf16 v[44:47], v[202:205], v[156:159], v[44:47]
	v_mfma_f32_16x16x32_bf16 v[36:39], v[188:191], v[164:167], v[36:39]
	v_mfma_f32_16x16x32_bf16 v[28:31], v[202:205], v[164:167], v[28:31]
	v_mfma_f32_16x16x32_bf16 v[20:23], v[188:191], v[172:175], v[20:23]
	v_mfma_f32_16x16x32_bf16 v[12:15], v[202:205], v[172:175], v[12:15]
	v_mfma_f32_16x16x32_bf16 v[4:7], v[188:191], v[180:183], v[4:7]
	v_mfma_f32_16x16x32_bf16 v[0:3], v[202:205], v[180:183], v[0:3]
	s_setprio 0
	s_add_i32 s42, s42, 2
	s_add_u32 s26, s26, 0x100
	s_addc_u32 s27, s27, 0
	s_add_u32 s28, s28, 0x100
	s_addc_u32 s29, s29, 0
	s_cmp_gt_u32 s42, 39
	s_barrier
	s_cbranch_scc0 .LBB0_2188
	s_mov_b32 s26, 0
	s_and_b64 vcc, exec, s[40:41]
	v_mbcnt_lo_u32_b32 v136, -1, s26
	v_mbcnt_hi_u32_b32 v136, -1, v136
	s_lshl_b32 s26, s55, 8
	s_add_i32 s26, s26, s47
	v_and_or_b32 v138, v136, 15, s26
	s_lshl_b32 s26, s56, 8
	v_ashrrev_i32_e32 v136, 2, v136
	s_or_b32 s26, s26, s48
	v_and_b32_e32 v136, -4, v136
	v_add_u32_e32 v136, s26, v136
	v_ashrrev_i32_e32 v137, 31, v136
	v_lshlrev_b64 v[136:137], 1, v[136:137]
	v_ashrrev_i32_e32 v139, 31, v138
	v_lshl_add_u64 v[140:141], s[0:1], 0, v[136:137]
	v_lshlrev_b64 v[198:199], 11, v[138:139]
	v_lshl_add_u64 v[142:143], v[140:141], 0, v[198:199]
	global_load_dwordx2 v[200:201], v[142:143], off
	global_load_dwordx2 v[202:203], v[142:143], off offset:32
	global_load_dwordx2 v[204:205], v[142:143], off offset:256
	global_load_dwordx2 v[206:207], v[142:143], off offset:288
	v_or_b32_e32 v142, 16, v138
	v_ashrrev_i32_e32 v143, 31, v142
	v_lshlrev_b64 v[208:209], 11, v[142:143]
	v_lshl_add_u64 v[142:143], v[140:141], 0, v[208:209]
	global_load_dwordx2 v[210:211], v[142:143], off
	global_load_dwordx2 v[212:213], v[142:143], off offset:32
	global_load_dwordx2 v[214:215], v[142:143], off offset:256
	global_load_dwordx2 v[216:217], v[142:143], off offset:288
	v_or_b32_e32 v142, 32, v138
	v_or_b32_e32 v138, 48, v138
	v_ashrrev_i32_e32 v143, 31, v142
	v_ashrrev_i32_e32 v139, 31, v138
	v_lshlrev_b64 v[218:219], 11, v[142:143]
	v_lshlrev_b64 v[186:187], 11, v[138:139]
	s_mov_b64 s[26:27], 0x40000
	v_lshl_add_u64 v[142:143], v[140:141], 0, v[218:219]
	v_lshl_add_u64 v[138:139], v[140:141], 0, v[186:187]
	v_lshl_add_u64 v[176:177], v[198:199], 0, s[26:27]
	s_mov_b64 s[26:27], 0x48000
	global_load_dwordx2 v[220:221], v[142:143], off
	global_load_dwordx2 v[192:193], v[142:143], off offset:32
	global_load_dwordx2 v[190:191], v[142:143], off offset:256
	global_load_dwordx2 v[188:189], v[142:143], off offset:288
	global_load_dwordx2 v[184:185], v[138:139], off
	global_load_dwordx2 v[182:183], v[138:139], off offset:32
	global_load_dwordx2 v[180:181], v[138:139], off offset:256
	global_load_dwordx2 v[178:179], v[138:139], off offset:288
	v_lshl_add_u64 v[138:139], v[140:141], 0, v[176:177]
	v_lshl_add_u64 v[166:167], v[198:199], 0, s[26:27]
	s_mov_b64 s[26:27], 0x50000
	global_load_dwordx2 v[174:175], v[138:139], off
	global_load_dwordx2 v[172:173], v[138:139], off offset:32
	global_load_dwordx2 v[170:171], v[138:139], off offset:256
	global_load_dwordx2 v[168:169], v[138:139], off offset:288
	v_lshl_add_u64 v[138:139], v[140:141], 0, v[166:167]
	v_lshl_add_u64 v[156:157], v[198:199], 0, s[26:27]
	s_mov_b64 s[26:27], 0x58000
	global_load_dwordx2 v[164:165], v[138:139], off
	global_load_dwordx2 v[162:163], v[138:139], off offset:32
	global_load_dwordx2 v[160:161], v[138:139], off offset:256
	global_load_dwordx2 v[158:159], v[138:139], off offset:288
	v_lshl_add_u64 v[138:139], v[140:141], 0, v[156:157]
	v_lshl_add_u64 v[146:147], v[198:199], 0, s[26:27]
	global_load_dwordx2 v[154:155], v[138:139], off
	global_load_dwordx2 v[152:153], v[138:139], off offset:32
	global_load_dwordx2 v[150:151], v[138:139], off offset:256
	global_load_dwordx2 v[148:149], v[138:139], off offset:288
	v_lshl_add_u64 v[138:139], v[140:141], 0, v[146:147]
	global_load_dwordx2 v[144:145], v[138:139], off
	global_load_dwordx2 v[142:143], v[138:139], off offset:32
	global_load_dwordx2 v[140:141], v[138:139], off offset:256
	s_nop 0
	global_load_dwordx2 v[138:139], v[138:139], off offset:288
	v_mbcnt_lo_u32_b32 v232, -1, 0
	v_mbcnt_hi_u32_b32 v232, -1, v232
	v_and_b32_e32 v232, 16, v232
	v_cmp_ne_u32_e64 s[98:99], 0, v232
	s_nop 1
	v_cndmask_b32_e64 v233, 0, -1, s[98:99]
	v_cndmask_b32_e64 v232, 32, -8, s[98:99]
	v_add_co_u32_e64 v136, s[98:99], v136, v232
	s_nop 1
	v_addc_co_u32_e64 v137, s[98:99], v137, v233, s[98:99]
	v_lshl_add_u64 v[198:199], s[4:5], 0, v[198:199]
	v_lshl_add_u64 v[198:199], v[198:199], 0, v[136:137]
	s_mov_b32 s56, s53
	s_mov_b32 s55, s54
	s_mov_b64 s[28:29], s[24:25]
	s_mov_b64 s[26:27], s[22:23]
	s_waitcnt vmcnt(0)
	s_nop 0
	v_lshlrev_b32_e32 v222, 16, v200
	v_and_b32_e32 v223, 0xffff0000, v200
	v_lshlrev_b32_e32 v200, 16, v201
	v_and_b32_e32 v201, 0xffff0000, v201
	v_pk_fma_f32 v[126:127], v[200:201], s[20:21], v[126:127] op_sel_hi:[1,0,1]
	v_pk_fma_f32 v[124:125], v[222:223], s[20:21], v[124:125] op_sel_hi:[1,0,1]
	s_nop 0
	v_cvt_pk_bf16_f32 v226, v124, v125
	v_cvt_pk_bf16_f32 v227, v126, v127
	v_lshlrev_b32_e32 v124, 16, v202
	v_and_b32_e32 v125, 0xffff0000, v202
	v_lshlrev_b32_e32 v126, 16, v203
	v_and_b32_e32 v127, 0xffff0000, v203
	v_pk_fma_f32 v[122:123], v[126:127], s[20:21], v[122:123] op_sel_hi:[1,0,1]
	v_pk_fma_f32 v[120:121], v[124:125], s[20:21], v[120:121] op_sel_hi:[1,0,1]
	s_nop 0
	v_cvt_pk_bf16_f32 v224, v120, v121
	v_cvt_pk_bf16_f32 v225, v122, v123
	s_nop 1
	v_permlane16_swap_b32_e32 v224, v226
	v_permlane16_swap_b32_e32 v225, v227
	global_store_dwordx4 v[198:199], v[224:227], off
	v_lshlrev_b32_e32 v120, 16, v204
	v_and_b32_e32 v121, 0xffff0000, v204
	v_lshlrev_b32_e32 v122, 16, v205
	v_and_b32_e32 v123, 0xffff0000, v205
	v_pk_fma_f32 v[118:119], v[122:123], s[20:21], v[118:119] op_sel_hi:[1,0,1]
	v_pk_fma_f32 v[116:117], v[120:121], s[20:21], v[116:117] op_sel_hi:[1,0,1]
	s_nop 0
	v_cvt_pk_bf16_f32 v230, v116, v117
	v_cvt_pk_bf16_f32 v231, v118, v119
	v_lshlrev_b32_e32 v116, 16, v206
	v_and_b32_e32 v117, 0xffff0000, v206
	v_lshlrev_b32_e32 v118, 16, v207
	v_and_b32_e32 v119, 0xffff0000, v207
	v_pk_fma_f32 v[110:111], v[118:119], s[20:21], v[110:111] op_sel_hi:[1,0,1]
	v_pk_fma_f32 v[108:109], v[116:117], s[20:21], v[108:109] op_sel_hi:[1,0,1]
	v_lshlrev_b32_e32 v116, 16, v211
	v_cvt_pk_bf16_f32 v228, v108, v109
	v_cvt_pk_bf16_f32 v229, v110, v111
	v_lshlrev_b32_e32 v110, 16, v210
	v_and_b32_e32 v111, 0xffff0000, v210
	v_and_b32_e32 v117, 0xffff0000, v211
	s_nop 1
	v_permlane16_swap_b32_e32 v228, v230
	v_permlane16_swap_b32_e32 v229, v231
	global_store_dwordx4 v[198:199], v[228:231], off offset:256
	v_lshl_add_u64 v[108:109], s[4:5], 0, v[208:209]
	v_pk_fma_f32 v[114:115], v[116:117], s[20:21], v[114:115] op_sel_hi:[1,0,1]
	v_pk_fma_f32 v[110:111], v[110:111], s[20:21], v[112:113] op_sel_hi:[1,0,1]
	v_lshl_add_u64 v[108:109], v[108:109], 0, v[136:137]
	v_cvt_pk_bf16_f32 v226, v110, v111
	v_cvt_pk_bf16_f32 v227, v114, v115
	v_lshlrev_b32_e32 v110, 16, v212
	v_and_b32_e32 v111, 0xffff0000, v212
	v_lshlrev_b32_e32 v112, 16, v213
	v_and_b32_e32 v113, 0xffff0000, v213
	v_pk_fma_f32 v[106:107], v[112:113], s[20:21], v[106:107] op_sel_hi:[1,0,1]
	v_pk_fma_f32 v[104:105], v[110:111], s[20:21], v[104:105] op_sel_hi:[1,0,1]
	s_nop 0
	v_cvt_pk_bf16_f32 v224, v104, v105
	v_cvt_pk_bf16_f32 v225, v106, v107
	s_nop 1
	v_permlane16_swap_b32_e32 v224, v226
	v_permlane16_swap_b32_e32 v225, v227
	global_store_dwordx4 v[108:109], v[224:227], off
	v_lshlrev_b32_e32 v104, 16, v214
	v_and_b32_e32 v105, 0xffff0000, v214
	v_lshlrev_b32_e32 v106, 16, v215
	v_and_b32_e32 v107, 0xffff0000, v215
	v_pk_fma_f32 v[102:103], v[106:107], s[20:21], v[102:103] op_sel_hi:[1,0,1]
	v_pk_fma_f32 v[100:101], v[104:105], s[20:21], v[100:101] op_sel_hi:[1,0,1]
	s_nop 0
	v_cvt_pk_bf16_f32 v230, v100, v101
	v_cvt_pk_bf16_f32 v231, v102, v103
	v_lshlrev_b32_e32 v100, 16, v216
	v_and_b32_e32 v101, 0xffff0000, v216
	v_lshlrev_b32_e32 v102, 16, v217
	v_and_b32_e32 v103, 0xffff0000, v217
	v_pk_fma_f32 v[94:95], v[102:103], s[20:21], v[94:95] op_sel_hi:[1,0,1]
	v_pk_fma_f32 v[92:93], v[100:101], s[20:21], v[92:93] op_sel_hi:[1,0,1]
	v_lshlrev_b32_e32 v100, 16, v221
	v_cvt_pk_bf16_f32 v228, v92, v93
	v_cvt_pk_bf16_f32 v229, v94, v95
	v_lshlrev_b32_e32 v94, 16, v220
	v_and_b32_e32 v95, 0xffff0000, v220
	v_and_b32_e32 v101, 0xffff0000, v221
	s_nop 1
	v_permlane16_swap_b32_e32 v228, v230
	v_permlane16_swap_b32_e32 v229, v231
	global_store_dwordx4 v[108:109], v[228:231], off offset:256
	v_lshl_add_u64 v[92:93], s[4:5], 0, v[218:219]
	v_pk_fma_f32 v[98:99], v[100:101], s[20:21], v[98:99] op_sel_hi:[1,0,1]
	v_pk_fma_f32 v[94:95], v[94:95], s[20:21], v[96:97] op_sel_hi:[1,0,1]
	v_lshl_add_u64 v[92:93], v[92:93], 0, v[136:137]
	v_cvt_pk_bf16_f32 v226, v94, v95
	v_cvt_pk_bf16_f32 v227, v98, v99
	v_lshlrev_b32_e32 v94, 16, v192
	v_and_b32_e32 v95, 0xffff0000, v192
	v_lshlrev_b32_e32 v96, 16, v193
	v_and_b32_e32 v97, 0xffff0000, v193
	v_pk_fma_f32 v[90:91], v[96:97], s[20:21], v[90:91] op_sel_hi:[1,0,1]
	v_pk_fma_f32 v[88:89], v[94:95], s[20:21], v[88:89] op_sel_hi:[1,0,1]
	s_nop 0
	v_cvt_pk_bf16_f32 v224, v88, v89
	v_cvt_pk_bf16_f32 v225, v90, v91
	s_nop 1
	v_permlane16_swap_b32_e32 v224, v226
	v_permlane16_swap_b32_e32 v225, v227
	global_store_dwordx4 v[92:93], v[224:227], off
	v_lshlrev_b32_e32 v88, 16, v190
	v_and_b32_e32 v89, 0xffff0000, v190
	v_lshlrev_b32_e32 v90, 16, v191
	v_and_b32_e32 v91, 0xffff0000, v191
	v_pk_fma_f32 v[86:87], v[90:91], s[20:21], v[86:87] op_sel_hi:[1,0,1]
	v_pk_fma_f32 v[84:85], v[88:89], s[20:21], v[84:85] op_sel_hi:[1,0,1]
	s_nop 0
	v_cvt_pk_bf16_f32 v230, v84, v85
	v_cvt_pk_bf16_f32 v231, v86, v87
	v_lshlrev_b32_e32 v84, 16, v188
	v_and_b32_e32 v85, 0xffff0000, v188
	v_lshlrev_b32_e32 v86, 16, v189
	v_and_b32_e32 v87, 0xffff0000, v189
	v_pk_fma_f32 v[78:79], v[86:87], s[20:21], v[78:79] op_sel_hi:[1,0,1]
	v_pk_fma_f32 v[76:77], v[84:85], s[20:21], v[76:77] op_sel_hi:[1,0,1]
	v_lshlrev_b32_e32 v84, 16, v185
	v_cvt_pk_bf16_f32 v228, v76, v77
	v_cvt_pk_bf16_f32 v229, v78, v79
	v_lshlrev_b32_e32 v78, 16, v184
	v_and_b32_e32 v79, 0xffff0000, v184
	v_and_b32_e32 v85, 0xffff0000, v185
	s_nop 1
	v_permlane16_swap_b32_e32 v228, v230
	v_permlane16_swap_b32_e32 v229, v231
	global_store_dwordx4 v[92:93], v[228:231], off offset:256
	v_lshl_add_u64 v[76:77], s[4:5], 0, v[186:187]
	v_pk_fma_f32 v[82:83], v[84:85], s[20:21], v[82:83] op_sel_hi:[1,0,1]
	v_pk_fma_f32 v[78:79], v[78:79], s[20:21], v[80:81] op_sel_hi:[1,0,1]
	v_lshl_add_u64 v[76:77], v[76:77], 0, v[136:137]
	v_cvt_pk_bf16_f32 v226, v78, v79
	v_cvt_pk_bf16_f32 v227, v82, v83
	v_lshlrev_b32_e32 v78, 16, v182
	v_and_b32_e32 v79, 0xffff0000, v182
	v_lshlrev_b32_e32 v80, 16, v183
	v_and_b32_e32 v81, 0xffff0000, v183
	v_pk_fma_f32 v[74:75], v[80:81], s[20:21], v[74:75] op_sel_hi:[1,0,1]
	v_pk_fma_f32 v[72:73], v[78:79], s[20:21], v[72:73] op_sel_hi:[1,0,1]
	s_nop 0
	v_cvt_pk_bf16_f32 v224, v72, v73
	v_cvt_pk_bf16_f32 v225, v74, v75
	s_nop 1
	v_permlane16_swap_b32_e32 v224, v226
	v_permlane16_swap_b32_e32 v225, v227
	global_store_dwordx4 v[76:77], v[224:227], off
	v_lshlrev_b32_e32 v72, 16, v180
	v_and_b32_e32 v73, 0xffff0000, v180
	v_lshlrev_b32_e32 v74, 16, v181
	v_and_b32_e32 v75, 0xffff0000, v181
	v_pk_fma_f32 v[70:71], v[74:75], s[20:21], v[70:71] op_sel_hi:[1,0,1]
	v_pk_fma_f32 v[68:69], v[72:73], s[20:21], v[68:69] op_sel_hi:[1,0,1]
	s_nop 0
	v_cvt_pk_bf16_f32 v230, v68, v69
	v_cvt_pk_bf16_f32 v231, v70, v71
	v_lshlrev_b32_e32 v68, 16, v178
	v_and_b32_e32 v69, 0xffff0000, v178
	v_lshlrev_b32_e32 v70, 16, v179
	v_and_b32_e32 v71, 0xffff0000, v179
	v_pk_fma_f32 v[66:67], v[70:71], s[20:21], v[66:67] op_sel_hi:[1,0,1]
	v_pk_fma_f32 v[64:65], v[68:69], s[20:21], v[64:65] op_sel_hi:[1,0,1]
	v_lshlrev_b32_e32 v68, 16, v175
	v_cvt_pk_bf16_f32 v228, v64, v65
	v_cvt_pk_bf16_f32 v229, v66, v67
	v_lshlrev_b32_e32 v66, 16, v174
	v_and_b32_e32 v67, 0xffff0000, v174
	v_and_b32_e32 v69, 0xffff0000, v175
	s_nop 1
	v_permlane16_swap_b32_e32 v228, v230
	v_permlane16_swap_b32_e32 v229, v231
	global_store_dwordx4 v[76:77], v[228:231], off offset:256
	v_lshl_add_u64 v[64:65], s[4:5], 0, v[176:177]
	v_pk_fma_f32 v[62:63], v[68:69], s[20:21], v[62:63] op_sel_hi:[1,0,1]
	v_pk_fma_f32 v[60:61], v[66:67], s[20:21], v[60:61] op_sel_hi:[1,0,1]
	v_lshl_add_u64 v[64:65], v[64:65], 0, v[136:137]
	v_cvt_pk_bf16_f32 v226, v60, v61
	v_cvt_pk_bf16_f32 v227, v62, v63
	v_lshlrev_b32_e32 v60, 16, v172
	v_and_b32_e32 v61, 0xffff0000, v172
	v_lshlrev_b32_e32 v62, 16, v173
	v_and_b32_e32 v63, 0xffff0000, v173
	v_pk_fma_f32 v[58:59], v[62:63], s[20:21], v[58:59] op_sel_hi:[1,0,1]
	v_pk_fma_f32 v[56:57], v[60:61], s[20:21], v[56:57] op_sel_hi:[1,0,1]
	s_nop 0
	v_cvt_pk_bf16_f32 v224, v56, v57
	v_cvt_pk_bf16_f32 v225, v58, v59
	s_nop 1
	v_permlane16_swap_b32_e32 v224, v226
	v_permlane16_swap_b32_e32 v225, v227
	global_store_dwordx4 v[64:65], v[224:227], off
	v_lshlrev_b32_e32 v56, 16, v170
	v_and_b32_e32 v57, 0xffff0000, v170
	v_lshlrev_b32_e32 v58, 16, v171
	v_and_b32_e32 v59, 0xffff0000, v171
	v_pk_fma_f32 v[54:55], v[58:59], s[20:21], v[54:55] op_sel_hi:[1,0,1]
	v_pk_fma_f32 v[52:53], v[56:57], s[20:21], v[52:53] op_sel_hi:[1,0,1]
	s_nop 0
	v_cvt_pk_bf16_f32 v230, v52, v53
	v_cvt_pk_bf16_f32 v231, v54, v55
	v_lshlrev_b32_e32 v52, 16, v168
	v_and_b32_e32 v53, 0xffff0000, v168
	v_lshlrev_b32_e32 v54, 16, v169
	v_and_b32_e32 v55, 0xffff0000, v169
	v_pk_fma_f32 v[46:47], v[54:55], s[20:21], v[46:47] op_sel_hi:[1,0,1]
	v_pk_fma_f32 v[44:45], v[52:53], s[20:21], v[44:45] op_sel_hi:[1,0,1]
	v_lshlrev_b32_e32 v52, 16, v165
	v_cvt_pk_bf16_f32 v228, v44, v45
	v_cvt_pk_bf16_f32 v229, v46, v47
	v_lshlrev_b32_e32 v46, 16, v164
	v_and_b32_e32 v47, 0xffff0000, v164
	v_and_b32_e32 v53, 0xffff0000, v165
	s_nop 1
	v_permlane16_swap_b32_e32 v228, v230
	v_permlane16_swap_b32_e32 v229, v231
	global_store_dwordx4 v[64:65], v[228:231], off offset:256
	v_lshl_add_u64 v[44:45], s[4:5], 0, v[166:167]
	v_pk_fma_f32 v[50:51], v[52:53], s[20:21], v[50:51] op_sel_hi:[1,0,1]
	v_pk_fma_f32 v[46:47], v[46:47], s[20:21], v[48:49] op_sel_hi:[1,0,1]
	v_lshl_add_u64 v[44:45], v[44:45], 0, v[136:137]
	v_cvt_pk_bf16_f32 v226, v46, v47
	v_cvt_pk_bf16_f32 v227, v50, v51
	v_lshlrev_b32_e32 v46, 16, v162
	v_and_b32_e32 v47, 0xffff0000, v162
	v_lshlrev_b32_e32 v48, 16, v163
	v_and_b32_e32 v49, 0xffff0000, v163
	v_pk_fma_f32 v[42:43], v[48:49], s[20:21], v[42:43] op_sel_hi:[1,0,1]
	v_pk_fma_f32 v[40:41], v[46:47], s[20:21], v[40:41] op_sel_hi:[1,0,1]
	s_nop 0
	v_cvt_pk_bf16_f32 v224, v40, v41
	v_cvt_pk_bf16_f32 v225, v42, v43
	s_nop 1
	v_permlane16_swap_b32_e32 v224, v226
	v_permlane16_swap_b32_e32 v225, v227
	global_store_dwordx4 v[44:45], v[224:227], off
	v_lshlrev_b32_e32 v40, 16, v160
	v_and_b32_e32 v41, 0xffff0000, v160
	v_lshlrev_b32_e32 v42, 16, v161
	v_and_b32_e32 v43, 0xffff0000, v161
	v_pk_fma_f32 v[38:39], v[42:43], s[20:21], v[38:39] op_sel_hi:[1,0,1]
	v_pk_fma_f32 v[36:37], v[40:41], s[20:21], v[36:37] op_sel_hi:[1,0,1]
	s_nop 0
	v_cvt_pk_bf16_f32 v230, v36, v37
	v_cvt_pk_bf16_f32 v231, v38, v39
	v_lshlrev_b32_e32 v36, 16, v158
	v_and_b32_e32 v37, 0xffff0000, v158
	v_lshlrev_b32_e32 v38, 16, v159
	v_and_b32_e32 v39, 0xffff0000, v159
	v_pk_fma_f32 v[30:31], v[38:39], s[20:21], v[30:31] op_sel_hi:[1,0,1]
	v_pk_fma_f32 v[28:29], v[36:37], s[20:21], v[28:29] op_sel_hi:[1,0,1]
	v_lshlrev_b32_e32 v36, 16, v155
	v_cvt_pk_bf16_f32 v228, v28, v29
	v_cvt_pk_bf16_f32 v229, v30, v31
	v_lshlrev_b32_e32 v30, 16, v154
	v_and_b32_e32 v31, 0xffff0000, v154
	v_and_b32_e32 v37, 0xffff0000, v155
	s_nop 1
	v_permlane16_swap_b32_e32 v228, v230
	v_permlane16_swap_b32_e32 v229, v231
	global_store_dwordx4 v[44:45], v[228:231], off offset:256
	v_lshl_add_u64 v[28:29], s[4:5], 0, v[156:157]
	v_pk_fma_f32 v[34:35], v[36:37], s[20:21], v[34:35] op_sel_hi:[1,0,1]
	v_pk_fma_f32 v[30:31], v[30:31], s[20:21], v[32:33] op_sel_hi:[1,0,1]
	v_lshl_add_u64 v[28:29], v[28:29], 0, v[136:137]
	v_cvt_pk_bf16_f32 v226, v30, v31
	v_cvt_pk_bf16_f32 v227, v34, v35
	v_lshlrev_b32_e32 v30, 16, v152
	v_and_b32_e32 v31, 0xffff0000, v152
	v_lshlrev_b32_e32 v32, 16, v153
	v_and_b32_e32 v33, 0xffff0000, v153
	v_pk_fma_f32 v[26:27], v[32:33], s[20:21], v[26:27] op_sel_hi:[1,0,1]
	v_pk_fma_f32 v[24:25], v[30:31], s[20:21], v[24:25] op_sel_hi:[1,0,1]
	s_nop 0
	v_cvt_pk_bf16_f32 v224, v24, v25
	v_cvt_pk_bf16_f32 v225, v26, v27
	s_nop 1
	v_permlane16_swap_b32_e32 v224, v226
	v_permlane16_swap_b32_e32 v225, v227
	global_store_dwordx4 v[28:29], v[224:227], off
	v_lshlrev_b32_e32 v24, 16, v150
	v_and_b32_e32 v25, 0xffff0000, v150
	v_lshlrev_b32_e32 v26, 16, v151
	v_and_b32_e32 v27, 0xffff0000, v151
	v_pk_fma_f32 v[22:23], v[26:27], s[20:21], v[22:23] op_sel_hi:[1,0,1]
	v_pk_fma_f32 v[20:21], v[24:25], s[20:21], v[20:21] op_sel_hi:[1,0,1]
	s_nop 0
	v_cvt_pk_bf16_f32 v230, v20, v21
	v_cvt_pk_bf16_f32 v231, v22, v23
	v_lshlrev_b32_e32 v20, 16, v148
	v_and_b32_e32 v21, 0xffff0000, v148
	v_lshlrev_b32_e32 v22, 16, v149
	v_and_b32_e32 v23, 0xffff0000, v149
	v_pk_fma_f32 v[14:15], v[22:23], s[20:21], v[14:15] op_sel_hi:[1,0,1]
	v_pk_fma_f32 v[12:13], v[20:21], s[20:21], v[12:13] op_sel_hi:[1,0,1]
	v_lshlrev_b32_e32 v20, 16, v145
	v_cvt_pk_bf16_f32 v228, v12, v13
	v_cvt_pk_bf16_f32 v229, v14, v15
	v_lshlrev_b32_e32 v14, 16, v144
	v_and_b32_e32 v15, 0xffff0000, v144
	v_and_b32_e32 v21, 0xffff0000, v145
	s_nop 1
	v_permlane16_swap_b32_e32 v228, v230
	v_permlane16_swap_b32_e32 v229, v231
	global_store_dwordx4 v[28:29], v[228:231], off offset:256
	v_lshl_add_u64 v[12:13], s[4:5], 0, v[146:147]
	v_pk_fma_f32 v[18:19], v[20:21], s[20:21], v[18:19] op_sel_hi:[1,0,1]
	v_pk_fma_f32 v[14:15], v[14:15], s[20:21], v[16:17] op_sel_hi:[1,0,1]
	v_lshl_add_u64 v[12:13], v[12:13], 0, v[136:137]
	v_cvt_pk_bf16_f32 v226, v14, v15
	v_cvt_pk_bf16_f32 v227, v18, v19
	v_lshlrev_b32_e32 v14, 16, v142
	v_and_b32_e32 v15, 0xffff0000, v142
	v_lshlrev_b32_e32 v16, 16, v143
	v_and_b32_e32 v17, 0xffff0000, v143
	v_pk_fma_f32 v[10:11], v[16:17], s[20:21], v[10:11] op_sel_hi:[1,0,1]
	v_pk_fma_f32 v[8:9], v[14:15], s[20:21], v[8:9] op_sel_hi:[1,0,1]
	s_nop 0
	v_cvt_pk_bf16_f32 v224, v8, v9
	v_cvt_pk_bf16_f32 v225, v10, v11
	s_nop 1
	v_permlane16_swap_b32_e32 v224, v226
	v_permlane16_swap_b32_e32 v225, v227
	global_store_dwordx4 v[12:13], v[224:227], off
	v_lshlrev_b32_e32 v8, 16, v140
	v_and_b32_e32 v9, 0xffff0000, v140
	v_lshlrev_b32_e32 v10, 16, v141
	v_and_b32_e32 v11, 0xffff0000, v141
	v_pk_fma_f32 v[6:7], v[10:11], s[20:21], v[6:7] op_sel_hi:[1,0,1]
	v_pk_fma_f32 v[4:5], v[8:9], s[20:21], v[4:5] op_sel_hi:[1,0,1]
	s_nop 0
	v_cvt_pk_bf16_f32 v230, v4, v5
	v_cvt_pk_bf16_f32 v231, v6, v7
	v_lshlrev_b32_e32 v4, 16, v138
	v_and_b32_e32 v5, 0xffff0000, v138
	v_lshlrev_b32_e32 v6, 16, v139
	v_and_b32_e32 v7, 0xffff0000, v139
	v_pk_fma_f32 v[2:3], v[6:7], s[20:21], v[2:3] op_sel_hi:[1,0,1]
	v_pk_fma_f32 v[0:1], v[4:5], s[20:21], v[0:1] op_sel_hi:[1,0,1]
	s_nop 0
	v_cvt_pk_bf16_f32 v228, v0, v1
	v_cvt_pk_bf16_f32 v229, v2, v3
	s_nop 1
	v_permlane16_swap_b32_e32 v228, v230
	v_permlane16_swap_b32_e32 v229, v231
	global_store_dwordx4 v[12:13], v[228:231], off offset:256
	s_cbranch_vccz .LBB0_2177
	s_waitcnt vmcnt(0)
	s_cmpk_gt_u32 s31, 0xff
	s_cbranch_scc1 .LBB0_2192
	s_barrier
